# attention: staggered group's K/V LDS writes moved further ahead of its mid-body barrier
# speedup vs baseline: 1.0051x; 1.0051x over previous
; #define LAS __attribute__((address_space(3)))
; __device__ __forceinline__ float fexp2(float x) { return __builtin_amdgcn_exp2f(x); }
; template <int MODE>
; __device__ __forceinline__ void attn_pv(const LAS unsigned char* vb_, f32x16 (&st)[2], f32x16 (&ot)[2], float& mrun, float& lsum, const int ql, const int hf, const int lane) {
;     if (MODE != 1) {
;     float mx = max3f(st[0][0], st[1][0], st[0][1]), my = max3f(st[1][1], st[0][2], st[1][2]);
; #pragma unroll
;     for (int i = 3; i < 15; i += 2) { mx = max3f(mx, st[0][i], st[1][i]); my = max3f(my, st[0][i + 1], st[1][i + 1]); }
;     mx = max3f(mx, st[0][15], st[1][15]); mx = max3f(mx, my, my);
;     if (__builtin_amdgcn_ballot_w64(mx > mrun + 8.0f) != 0ull) {
;         mx = fmaxf(mx, shx32(mx, lane));
;         const float mnew = (mx > mrun + 8.0f) ? mx : mrun;
;         const float alpha = fexp2(mrun - mnew);
;         mrun = mnew; lsum *= alpha;
; #pragma unroll
;         for (int i = 0; i < 16; ++i) { ot[0][i] *= alpha; ot[1][i] *= alpha; }
;     }
;     float ps = 0.f;
; #pragma unroll
;     for (int kb = 0; kb < 2; ++kb)
; #pragma unroll
;         for (int i = 0; i < 16; ++i) { const float p = fexp2(st[kb][i] - mrun); st[kb][i] = p; ps += p; }
;     lsum += ps;
;     } else lsum += st[0][0];
; #pragma unroll
;     for (int kb = 0; kb < 2; ++kb)
; #pragma unroll
;         for (int sI = 0; sI < 2; ++sI) {
;             u32x4 pw = {pk_bf16(st[kb][8 * sI + 0], st[kb][8 * sI + 1]), pk_bf16(st[kb][8 * sI + 2], st[kb][8 * sI + 3]),
;                         pk_bf16(st[kb][8 * sI + 4], st[kb][8 * sI + 5]), pk_bf16(st[kb][8 * sI + 6], st[kb][8 * sI + 7])};
;             const bf16x8 pf = __builtin_bit_cast(bf16x8, pw);
; #pragma unroll
;             for (int db = 0; db < 2; ++db) {
;                 const LAS unsigned char* vp = vb_ + (db * 32 + ql) * VROW + (kb * 32 + 16 * sI + 4 * hf) * 2;
;                 const u32x2 v0 = *(const LAS u32x2*)vp, v1 = *(const LAS u32x2*)(vp + 16);
;                 u32x4 vw = {v0[0], v0[1], v1[0], v1[1]};
;                 ot[db] = att_mma<MODE>(__builtin_bit_cast(bf16x8, vw), pf, ot[db]);
;             }
;         }
; }
; template <int MODE>
; __device__ __forceinline__ void attn_phase(const Args& a, bool do_ctx, LAS unsigned char* lds, const int wid_s) {
;     ...
;             if (t + 2 < nkt) ATT_WRITEK(kK, kR, 0);
;             ATT_WRITEV(vV, 1);
.Latt_eB_nors:
	v_sub_f32_e32 v48, v48, v143
	v_sub_f32_e32 v49, v49, v143
	v_sub_f32_e32 v50, v50, v143
	v_sub_f32_e32 v51, v51, v143
	v_sub_f32_e32 v52, v52, v143
	v_sub_f32_e32 v53, v53, v143
	v_sub_f32_e32 v54, v54, v143
	v_sub_f32_e32 v55, v55, v143
	v_exp_f32_e32 v48, v48
	v_exp_f32_e32 v49, v49
	v_exp_f32_e32 v50, v50
	v_exp_f32_e32 v51, v51
	v_exp_f32_e32 v52, v52
	v_exp_f32_e32 v53, v53
	v_exp_f32_e32 v54, v54
	v_exp_f32_e32 v55, v55
	s_waitcnt lgkmcnt(11)
	v_mfma_f32_32x32x16_bf16 v[80:95], v[64:67], v[112:115], 0
	v_cvt_pk_bf16_f32 v152, v48, v49
	v_cvt_pk_bf16_f32 v153, v50, v51
	v_cvt_pk_bf16_f32 v154, v52, v53
	v_cvt_pk_bf16_f32 v155, v54, v55
	v_mfma_f32_32x32x16_bf16 v[64:79], v[68:71], v[112:115], 0
	v_pk_add_f32 v[230:231], v[48:49], v[50:51]
	v_pk_add_f32 v[230:231], v[230:231], v[52:53]
	v_pk_add_f32 v[230:231], v[230:231], v[54:55]
	v_mfma_f32_32x32x16_bf16 v[80:95], v[168:171], v[96:99], v[80:95]
	v_sub_f32_e32 v56, v56, v143
	v_sub_f32_e32 v57, v57, v143
	v_sub_f32_e32 v58, v58, v143
	v_sub_f32_e32 v59, v59, v143
	v_sub_f32_e32 v60, v60, v143
	v_sub_f32_e32 v61, v61, v143
	v_sub_f32_e32 v62, v62, v143
	v_sub_f32_e32 v63, v63, v143
	v_mfma_f32_32x32x16_bf16 v[64:79], v[172:175], v[96:99], v[64:79]
	ds_read_b128 v[168:171], v165 offset:13440
	ds_read_b128 v[172:175], v165 offset:13472
	ds_read_b128 v[192:195], v165 offset:20096
	ds_read_b128 v[196:199], v165 offset:20128
	v_exp_f32_e32 v56, v56
	v_exp_f32_e32 v57, v57
	v_exp_f32_e32 v58, v58
	v_exp_f32_e32 v59, v59
	s_waitcnt lgkmcnt(11)
	v_mfma_f32_32x32x16_bf16 v[80:95], v[176:179], v[100:103], v[80:95]
	ds_read_b128 a[0:3], v240 offset:31328
	v_exp_f32_e32 v60, v60
	v_exp_f32_e32 v61, v61
	v_exp_f32_e32 v62, v62
	v_exp_f32_e32 v63, v63
	v_mfma_f32_32x32x16_bf16 v[64:79], v[184:187], v[100:103], v[64:79]
	v_mfma_f32_32x32x16_bf16 v[80:95], v[180:183], v[104:107], v[80:95]
	v_cvt_pk_bf16_f32 v48, v56, v57
	v_cvt_pk_bf16_f32 v49, v58, v59
	v_cvt_pk_bf16_f32 v50, v60, v61
	v_cvt_pk_bf16_f32 v51, v62, v63
	v_mfma_f32_32x32x16_bf16 v[64:79], v[188:191], v[104:107], v[64:79]
	s_andn2_b64 vcc, exec, s[10:11]
	s_cbranch_vccnz .Latt_wskip_eB1
	s_waitcnt vmcnt(2)
	ds_write_b128 v162, v[120:123]
	s_and_saveexec_b64 s[2:3], s[6:7]
	s_cbranch_execz .Latt_wk_eB1
	s_waitcnt vmcnt(1)
	ds_write_b128 v164, v[124:127] offset:128

; #define LAS __attribute__((address_space(3)))
; __device__ __forceinline__ unsigned pk_bf16(float lo, float hi) { unsigned r; asm("v_cvt_pk_bf16_f32 %0, %1, %2" : "=v"(r) : "v"(lo), "v"(hi)); return r; }
; __device__ __forceinline__ float fexp2(float x) { return __builtin_amdgcn_exp2f(x); }
; #define ATT_WRITEV(rv, buf) do { LAS u32x2* p_ = (LAS u32x2*)(ldsv + (buf) * VBUF + svt); u32x2 lo_ = {rv[0], rv[1]}, hi_ = {rv[2], rv[3]}; p_[0] = lo_; p_[1] = hi_; } while (0)
; template <int MODE>
; __device__ __forceinline__ void attn_pv(const LAS unsigned char* vb_, f32x16 (&st)[2], f32x16 (&ot)[2], float& mrun, float& lsum, const int ql, const int hf, const int lane) {
;     ...
;     float ps = 0.f;
; #pragma unroll
;     for (int kb = 0; kb < 2; ++kb)
; #pragma unroll
;         for (int i = 0; i < 16; ++i) { const float p = fexp2(st[kb][i] - mrun); st[kb][i] = p; ps += p; }
;     lsum += ps;
;     } else lsum += st[0][0];
; #pragma unroll
;     for (int kb = 0; kb < 2; ++kb)
; #pragma unroll
;         for (int sI = 0; sI < 2; ++sI) {
;             u32x4 pw = {pk_bf16(st[kb][8 * sI + 0], st[kb][8 * sI + 1]), pk_bf16(st[kb][8 * sI + 2], st[kb][8 * sI + 3]),
;                         pk_bf16(st[kb][8 * sI + 4], st[kb][8 * sI + 5]), pk_bf16(st[kb][8 * sI + 6], st[kb][8 * sI + 7])};
;             const bf16x8 pf = __builtin_bit_cast(bf16x8, pw);
; #pragma unroll
;             for (int db = 0; db < 2; ++db) {
;                 const LAS unsigned char* vp = vb_ + (db * 32 + ql) * VROW + (kb * 32 + 16 * sI + 4 * hf) * 2;
;                 const u32x2 v0 = *(const LAS u32x2*)vp, v1 = *(const LAS u32x2*)(vp + 16);
;                 u32x4 vw = {v0[0], v0[1], v1[0], v1[1]};
;                 ot[db] = att_mma<MODE>(__builtin_bit_cast(bf16x8, vw), pf, ot[db]);
;             }
;         }
; }
; template <int MODE>
; __device__ __forceinline__ void attn_phase(const Args& a, bool do_ctx, LAS unsigned char* lds, const int wid_s) {
;     ...
;             ATT_WRITEV(vV, 1);
;             __syncthreads();
.Latt_wskip_eB1:
	s_waitcnt vmcnt(0)
	ds_write2_b64 v251, v[128:129], v[130:131] offset1:2
	s_waitcnt lgkmcnt(10)
	v_mfma_f32_32x32x16_bf16 v[16:31], v[206:209], v[152:155], v[16:31]
	v_pk_add_f32 v[230:231], v[230:231], v[56:57]
	v_pk_add_f32 v[230:231], v[230:231], v[58:59]
	v_pk_add_f32 v[230:231], v[230:231], v[60:61]
	v_pk_add_f32 v[230:231], v[230:231], v[62:63]
	v_mfma_f32_32x32x16_bf16 v[0:15], v[210:213], v[152:155], v[0:15]
	v_sub_f32_e32 v32, v32, v143
	v_sub_f32_e32 v33, v33, v143
	v_sub_f32_e32 v34, v34, v143
	v_sub_f32_e32 v35, v35, v143
	v_sub_f32_e32 v36, v36, v143
	v_sub_f32_e32 v37, v37, v143
	v_sub_f32_e32 v38, v38, v143
	v_sub_f32_e32 v39, v39, v143
	v_exp_f32_e32 v32, v32
	v_exp_f32_e32 v33, v33
	v_exp_f32_e32 v34, v34
	v_exp_f32_e32 v35, v35
	s_waitcnt lgkmcnt(0)
	s_barrier
	v_mfma_f32_32x32x16_bf16 v[80:95], v[168:171], v[108:111], v[80:95]
	v_exp_f32_e32 v36, v36
	v_exp_f32_e32 v37, v37
	v_exp_f32_e32 v38, v38
	v_exp_f32_e32 v39, v39
	v_mfma_f32_32x32x16_bf16 v[16:31], v[214:217], v[48:51], v[16:31]
	v_mfma_f32_32x32x16_bf16 v[0:15], v[218:221], v[48:51], v[0:15]
	v_cvt_pk_bf16_f32 v152, v32, v33
	v_cvt_pk_bf16_f32 v153, v34, v35
	v_cvt_pk_bf16_f32 v154, v36, v37
	v_cvt_pk_bf16_f32 v155, v38, v39
	v_mfma_f32_32x32x16_bf16 v[64:79], v[192:195], v[108:111], v[64:79]
	v_pk_add_f32 v[230:231], v[230:231], v[32:33]
	v_pk_add_f32 v[230:231], v[230:231], v[34:35]
	v_pk_add_f32 v[230:231], v[230:231], v[36:37]
	v_pk_add_f32 v[230:231], v[230:231], v[38:39]
	v_mfma_f32_32x32x16_bf16 v[80:95], v[172:175], v[116:119], v[80:95]
	v_sub_f32_e32 v40, v40, v143
	v_sub_f32_e32 v41, v41, v143
	v_sub_f32_e32 v42, v42, v143
	v_sub_f32_e32 v43, v43, v143
	v_sub_f32_e32 v44, v44, v143
	v_sub_f32_e32 v45, v45, v143
	v_sub_f32_e32 v46, v46, v143
	v_sub_f32_e32 v47, v47, v143
	v_mfma_f32_32x32x16_bf16 v[64:79], v[196:199], v[116:119], v[64:79]
	v_exp_f32_e32 v40, v40
	v_exp_f32_e32 v41, v41
	v_exp_f32_e32 v42, v42
	v_exp_f32_e32 v43, v43
	v_mfma_f32_32x32x16_bf16 v[16:31], v[222:225], v[152:155], v[16:31]
	v_exp_f32_e32 v44, v44
	v_exp_f32_e32 v45, v45
	v_exp_f32_e32 v46, v46
	v_exp_f32_e32 v47, v47
	v_mfma_f32_32x32x16_bf16 v[0:15], v[226:229], v[152:155], v[0:15]
	v_cvt_pk_bf16_f32 v48, v40, v41
	v_cvt_pk_bf16_f32 v49, v42, v43
	v_cvt_pk_bf16_f32 v50, v44, v45
	v_cvt_pk_bf16_f32 v51, v46, v47
	v_pk_add_f32 v[230:231], v[230:231], v[40:41]
	v_pk_add_f32 v[230:231], v[230:231], v[42:43]
	v_pk_add_f32 v[230:231], v[230:231], v[44:45]
	v_pk_add_f32 v[230:231], v[230:231], v[46:47]
	v_add_f32_e32 v230, v230, v231
	v_add_f32_e32 v167, v167, v230
	v_mfma_f32_32x32x16_bf16 v[0:15], v[236:239], v[48:51], v[0:15]
	v_mfma_f32_32x32x16_bf16 v[16:31], a[0:3], v[48:51], v[16:31]
	s_not_b64 s[8:9], s[10:11]
	s_cmp_lt_u32 s12, s25
	s_cselect_b64 s[10:11], -1, 0
	s_cmp_ge_u32 s12, s25
	s_branch .Latt_otop

; #define LAS __attribute__((address_space(3)))
; __device__ __forceinline__ float fexp2(float x) { return __builtin_amdgcn_exp2f(x); }
; template <int MODE>
; __device__ __forceinline__ void attn_pv(const LAS unsigned char* vb_, f32x16 (&st)[2], f32x16 (&ot)[2], float& mrun, float& lsum, const int ql, const int hf, const int lane) {
;     if (MODE != 1) {
;     float mx = max3f(st[0][0], st[1][0], st[0][1]), my = max3f(st[1][1], st[0][2], st[1][2]);
; #pragma unroll
;     for (int i = 3; i < 15; i += 2) { mx = max3f(mx, st[0][i], st[1][i]); my = max3f(my, st[0][i + 1], st[1][i + 1]); }
;     mx = max3f(mx, st[0][15], st[1][15]); mx = max3f(mx, my, my);
;     if (__builtin_amdgcn_ballot_w64(mx > mrun + 8.0f) != 0ull) {
;         mx = fmaxf(mx, shx32(mx, lane));
;         const float mnew = (mx > mrun + 8.0f) ? mx : mrun;
;         const float alpha = fexp2(mrun - mnew);
;         mrun = mnew; lsum *= alpha;
; #pragma unroll
;         for (int i = 0; i < 16; ++i) { ot[0][i] *= alpha; ot[1][i] *= alpha; }
;     }
;     float ps = 0.f;
; #pragma unroll
;     for (int kb = 0; kb < 2; ++kb)
; #pragma unroll
;         for (int i = 0; i < 16; ++i) { const float p = fexp2(st[kb][i] - mrun); st[kb][i] = p; ps += p; }
;     lsum += ps;
;     } else lsum += st[0][0];
; #pragma unroll
;     for (int kb = 0; kb < 2; ++kb)
; #pragma unroll
;         for (int sI = 0; sI < 2; ++sI) {
;             u32x4 pw = {pk_bf16(st[kb][8 * sI + 0], st[kb][8 * sI + 1]), pk_bf16(st[kb][8 * sI + 2], st[kb][8 * sI + 3]),
;                         pk_bf16(st[kb][8 * sI + 4], st[kb][8 * sI + 5]), pk_bf16(st[kb][8 * sI + 6], st[kb][8 * sI + 7])};
;             const bf16x8 pf = __builtin_bit_cast(bf16x8, pw);
; #pragma unroll
;             for (int db = 0; db < 2; ++db) {
;                 const LAS unsigned char* vp = vb_ + (db * 32 + ql) * VROW + (kb * 32 + 16 * sI + 4 * hf) * 2;
;                 const u32x2 v0 = *(const LAS u32x2*)vp, v1 = *(const LAS u32x2*)(vp + 16);
;                 u32x4 vw = {v0[0], v0[1], v1[0], v1[1]};
;                 ot[db] = att_mma<MODE>(__builtin_bit_cast(bf16x8, vw), pf, ot[db]);
;             }
;         }
; }
; template <int MODE>
; __device__ __forceinline__ void attn_phase(const Args& a, bool do_ctx, LAS unsigned char* lds, const int wid_s) {
;     ...
;             if (t + 3 < nkt) ATT_WRITEK(kK, kR, 1);
;             if (t + 2 < nkt) ATT_WRITEV(vV, 0);
.Latt_oB_nors:
	v_sub_f32_e32 v80, v80, v143
	v_sub_f32_e32 v81, v81, v143
	v_sub_f32_e32 v82, v82, v143
	v_sub_f32_e32 v83, v83, v143
	v_sub_f32_e32 v84, v84, v143
	v_sub_f32_e32 v85, v85, v143
	v_sub_f32_e32 v86, v86, v143
	v_sub_f32_e32 v87, v87, v143
	v_exp_f32_e32 v80, v80
	v_exp_f32_e32 v81, v81
	v_exp_f32_e32 v82, v82
	v_exp_f32_e32 v83, v83
	v_exp_f32_e32 v84, v84
	v_exp_f32_e32 v85, v85
	v_exp_f32_e32 v86, v86
	v_exp_f32_e32 v87, v87
	s_waitcnt lgkmcnt(11)
	v_mfma_f32_32x32x16_bf16 v[48:63], v[32:35], v[112:115], 0
	v_cvt_pk_bf16_f32 v168, v80, v81
	v_cvt_pk_bf16_f32 v169, v82, v83
	v_cvt_pk_bf16_f32 v170, v84, v85
	v_cvt_pk_bf16_f32 v171, v86, v87
	v_mfma_f32_32x32x16_bf16 v[32:47], v[36:39], v[112:115], 0
	v_pk_add_f32 v[230:231], v[80:81], v[82:83]
	v_pk_add_f32 v[230:231], v[230:231], v[84:85]
	v_pk_add_f32 v[230:231], v[230:231], v[86:87]
	v_mfma_f32_32x32x16_bf16 v[48:63], v[152:155], v[96:99], v[48:63]
	v_sub_f32_e32 v88, v88, v143
	v_sub_f32_e32 v89, v89, v143
	v_sub_f32_e32 v90, v90, v143
	v_sub_f32_e32 v91, v91, v143
	v_sub_f32_e32 v92, v92, v143
	v_sub_f32_e32 v93, v93, v143
	v_sub_f32_e32 v94, v94, v143
	v_sub_f32_e32 v95, v95, v143
	v_mfma_f32_32x32x16_bf16 v[32:47], v[206:209], v[96:99], v[32:47]
	ds_read_b128 v[152:155], v165 offset:128
	ds_read_b128 v[206:209], v165 offset:160
	ds_read_b128 v[226:229], v165 offset:6784
	ds_read_b128 v[236:239], v165 offset:6816
	v_exp_f32_e32 v88, v88
	v_exp_f32_e32 v89, v89
	v_exp_f32_e32 v90, v90
	v_exp_f32_e32 v91, v91
	s_waitcnt lgkmcnt(11)
	v_mfma_f32_32x32x16_bf16 v[48:63], v[210:213], v[100:103], v[48:63]
	ds_read_b128 a[0:3], v240 offset:40544
	v_exp_f32_e32 v92, v92
	v_exp_f32_e32 v93, v93
	v_exp_f32_e32 v94, v94
	v_exp_f32_e32 v95, v95
	v_mfma_f32_32x32x16_bf16 v[32:47], v[218:221], v[100:103], v[32:47]
	v_mfma_f32_32x32x16_bf16 v[48:63], v[214:217], v[104:107], v[48:63]
	v_cvt_pk_bf16_f32 v80, v88, v89
	v_cvt_pk_bf16_f32 v81, v90, v91
	v_cvt_pk_bf16_f32 v82, v92, v93
	v_cvt_pk_bf16_f32 v83, v94, v95
	v_mfma_f32_32x32x16_bf16 v[32:47], v[222:225], v[104:107], v[32:47]
	s_andn2_b64 vcc, exec, s[10:11]
	s_cbranch_vccnz .Latt_wskip_oB1
	s_waitcnt vmcnt(1)
	ds_write_b128 v162, v[120:123] offset:13312
	s_and_saveexec_b64 s[2:3], s[6:7]
	s_cbranch_execz .Latt_wk_oB1
	s_waitcnt vmcnt(0)
	ds_write_b128 v164, v[124:127] offset:13440

; #define LAS __attribute__((address_space(3)))
; __device__ __forceinline__ unsigned pk_bf16(float lo, float hi) { unsigned r; asm("v_cvt_pk_bf16_f32 %0, %1, %2" : "=v"(r) : "v"(lo), "v"(hi)); return r; }
; __device__ __forceinline__ float fexp2(float x) { return __builtin_amdgcn_exp2f(x); }
; #define ATT_WRITEV(rv, buf) do { LAS u32x2* p_ = (LAS u32x2*)(ldsv + (buf) * VBUF + svt); u32x2 lo_ = {rv[0], rv[1]}, hi_ = {rv[2], rv[3]}; p_[0] = lo_; p_[1] = hi_; } while (0)
; template <int MODE>
; __device__ __forceinline__ void attn_pv(const LAS unsigned char* vb_, f32x16 (&st)[2], f32x16 (&ot)[2], float& mrun, float& lsum, const int ql, const int hf, const int lane) {
;     ...
;     float ps = 0.f;
; #pragma unroll
;     for (int kb = 0; kb < 2; ++kb)
; #pragma unroll
;         for (int i = 0; i < 16; ++i) { const float p = fexp2(st[kb][i] - mrun); st[kb][i] = p; ps += p; }
;     lsum += ps;
;     } else lsum += st[0][0];
; #pragma unroll
;     for (int kb = 0; kb < 2; ++kb)
; #pragma unroll
;         for (int sI = 0; sI < 2; ++sI) {
;             u32x4 pw = {pk_bf16(st[kb][8 * sI + 0], st[kb][8 * sI + 1]), pk_bf16(st[kb][8 * sI + 2], st[kb][8 * sI + 3]),
;                         pk_bf16(st[kb][8 * sI + 4], st[kb][8 * sI + 5]), pk_bf16(st[kb][8 * sI + 6], st[kb][8 * sI + 7])};
;             const bf16x8 pf = __builtin_bit_cast(bf16x8, pw);
; #pragma unroll
;             for (int db = 0; db < 2; ++db) {
;                 const LAS unsigned char* vp = vb_ + (db * 32 + ql) * VROW + (kb * 32 + 16 * sI + 4 * hf) * 2;
;                 const u32x2 v0 = *(const LAS u32x2*)vp, v1 = *(const LAS u32x2*)(vp + 16);
;                 u32x4 vw = {v0[0], v0[1], v1[0], v1[1]};
;                 ot[db] = att_mma<MODE>(__builtin_bit_cast(bf16x8, vw), pf, ot[db]);
;             }
;         }
; }
; template <int MODE>
; __device__ __forceinline__ void attn_phase(const Args& a, bool do_ctx, LAS unsigned char* lds, const int wid_s) {
;     ...
;             if (t + 2 < nkt) ATT_WRITEV(vV, 0);
;             __syncthreads();
;         }
.Latt_wskip_oB1:
	s_waitcnt vmcnt(0)
	ds_write2_b64 v141, v[128:129], v[130:131] offset1:2
	s_waitcnt lgkmcnt(10)
	v_mfma_f32_32x32x16_bf16 v[0:15], v[176:179], v[168:171], v[0:15]
	v_pk_add_f32 v[230:231], v[230:231], v[88:89]
	v_pk_add_f32 v[230:231], v[230:231], v[90:91]
	v_pk_add_f32 v[230:231], v[230:231], v[92:93]
	v_pk_add_f32 v[230:231], v[230:231], v[94:95]
	v_mfma_f32_32x32x16_bf16 v[16:31], v[180:183], v[168:171], v[16:31]
	v_sub_f32_e32 v64, v64, v143
	v_sub_f32_e32 v65, v65, v143
	v_sub_f32_e32 v66, v66, v143
	v_sub_f32_e32 v67, v67, v143
	v_sub_f32_e32 v68, v68, v143
	v_sub_f32_e32 v69, v69, v143
	v_sub_f32_e32 v70, v70, v143
	v_sub_f32_e32 v71, v71, v143
	v_exp_f32_e32 v64, v64
	v_exp_f32_e32 v65, v65
	v_exp_f32_e32 v66, v66
	v_exp_f32_e32 v67, v67
	s_waitcnt lgkmcnt(0)
	s_barrier
	v_mfma_f32_32x32x16_bf16 v[48:63], v[152:155], v[108:111], v[48:63]
	v_exp_f32_e32 v68, v68
	v_exp_f32_e32 v69, v69
	v_exp_f32_e32 v70, v70
	v_exp_f32_e32 v71, v71
	v_mfma_f32_32x32x16_bf16 v[0:15], v[184:187], v[80:83], v[0:15]
	v_mfma_f32_32x32x16_bf16 v[16:31], v[188:191], v[80:83], v[16:31]
	v_cvt_pk_bf16_f32 v168, v64, v65
	v_cvt_pk_bf16_f32 v169, v66, v67
	v_cvt_pk_bf16_f32 v170, v68, v69
	v_cvt_pk_bf16_f32 v171, v70, v71
	v_mfma_f32_32x32x16_bf16 v[32:47], v[226:229], v[108:111], v[32:47]
	v_pk_add_f32 v[230:231], v[230:231], v[64:65]
	v_pk_add_f32 v[230:231], v[230:231], v[66:67]
	v_pk_add_f32 v[230:231], v[230:231], v[68:69]
	v_pk_add_f32 v[230:231], v[230:231], v[70:71]
	v_mfma_f32_32x32x16_bf16 v[48:63], v[206:209], v[116:119], v[48:63]
	v_sub_f32_e32 v72, v72, v143
	v_sub_f32_e32 v73, v73, v143
	v_sub_f32_e32 v74, v74, v143
	v_sub_f32_e32 v75, v75, v143
	v_sub_f32_e32 v76, v76, v143
	v_sub_f32_e32 v77, v77, v143
	v_sub_f32_e32 v78, v78, v143
	v_sub_f32_e32 v79, v79, v143
	v_mfma_f32_32x32x16_bf16 v[32:47], v[236:239], v[116:119], v[32:47]
	v_exp_f32_e32 v72, v72
	v_exp_f32_e32 v73, v73
	v_exp_f32_e32 v74, v74
	v_exp_f32_e32 v75, v75
	v_mfma_f32_32x32x16_bf16 v[0:15], v[192:195], v[168:171], v[0:15]
	v_exp_f32_e32 v76, v76
	v_exp_f32_e32 v77, v77
	v_exp_f32_e32 v78, v78
	v_exp_f32_e32 v79, v79
	v_mfma_f32_32x32x16_bf16 v[16:31], v[196:199], v[168:171], v[16:31]
	v_cvt_pk_bf16_f32 v80, v72, v73
	v_cvt_pk_bf16_f32 v81, v74, v75
	v_cvt_pk_bf16_f32 v82, v76, v77
	v_cvt_pk_bf16_f32 v83, v78, v79
	v_pk_add_f32 v[230:231], v[230:231], v[72:73]
	v_pk_add_f32 v[230:231], v[230:231], v[74:75]
	v_pk_add_f32 v[230:231], v[230:231], v[76:77]
	v_pk_add_f32 v[230:231], v[230:231], v[78:79]
	v_add_f32_e32 v230, v230, v231
	v_add_f32_e32 v167, v167, v230
	v_mfma_f32_32x32x16_bf16 v[0:15], v[172:175], v[80:83], v[0:15]
	v_mfma_f32_32x32x16_bf16 v[16:31], a[0:3], v[80:83], v[16:31]
	s_add_u32 s80, s80, 0x20000
	s_addc_u32 s81, s81, 0
	s_add_u32 s82, s82, 0x2000
	s_addc_u32 s83, s83, 0
	s_add_u32 s84, s84, 0x100
	s_addc_u32 s85, s85, 0
	s_add_i32 s12, s12, 2
	s_branch .LBB0_435
